# work-queue tails: next round's queue atomic no longer waited right after issue (read at next round start)
# baseline (speedup 1.0000x reference)
.LBB0_835:
	s_or_b64 exec, exec, s[12:13]
	s_waitcnt vmcnt(0)
	v_readfirstlane_b32 s12, v3
	s_nop 1
	v_lshl_add_u32 v86, v2, 3, s12
	v_mov_b32_e32 v254, v86

.LBB0_839:
	s_andn2_b64 vcc, exec, s[2:3]
	s_mov_b64 s[16:17], -1
	s_cbranch_vccnz .LBB0_848
	s_and_saveexec_b64 s[18:19], s[8:9]
	s_cbranch_execz .Lqdef1
	s_waitcnt vmcnt(0)
	v_mov_b32_e32 v86, v254
.Lqdef1:
	v_mov_b32_e32 v2, s33
	ds_write_b32 v2, v86
	s_or_b64 exec, exec, s[18:19]
	v_mov_b32_e32 v2, s33
	s_waitcnt lgkmcnt(0)
	s_barrier
	ds_read_b32 v2, v2
	s_movk_i32 s20, 0x123f
	s_mov_b64 s[18:19], 0
	s_waitcnt lgkmcnt(0)
	s_barrier
	v_cmp_lt_i32_e32 vcc, s20, v2
	v_readfirstlane_b32 s14, v2
	v_readfirstlane_b32 s20, v0
	s_cbranch_vccnz .LBB0_849
	s_and_saveexec_b64 s[18:19], s[8:9]
	s_cbranch_execz .LBB0_847
	s_mov_b64 s[22:23], exec
	v_mbcnt_lo_u32_b32 v2, s22, 0
	v_mbcnt_hi_u32_b32 v2, s23, v2
	v_cmp_eq_u32_e32 vcc, 0, v2
	s_and_saveexec_b64 s[20:21], vcc
	s_cbranch_execz .LBB0_846
	s_bcnt1_i32_b64 s22, s[22:23]
	s_lshl_b32 s22, s22, 3
	v_mov_b32_e32 v3, s22
	global_atomic_add v254, v67, v3, s[0:1] sc0
.LBB0_846:
	s_or_b64 exec, exec, s[20:21]
.LBB0_847:
	s_or_b64 exec, exec, s[18:19]
	v_readlane_b32 s18, v248, 8
	s_add_i32 s20, s14, s18

.LBB0_1725:
	s_or_b64 exec, exec, s[14:15]
	s_waitcnt vmcnt(0)
	v_readfirstlane_b32 s14, v3
	s_nop 1
	v_lshl_add_u32 v67, v2, 3, s14
	v_mov_b32_e32 v254, v67

.LBB0_1729:
	s_and_b64 vcc, exec, s[0:1]
	s_mov_b64 s[20:21], -1
	s_cbranch_vccnz .LBB0_1738
	s_and_saveexec_b64 s[22:23], s[8:9]
	s_cbranch_execz .Lqdef2
	s_waitcnt vmcnt(0)
	v_mov_b32_e32 v67, v254
.Lqdef2:
	v_mov_b32_e32 v2, s43
	ds_write_b32 v2, v67
	s_or_b64 exec, exec, s[22:23]
	v_mov_b32_e32 v2, s43
	s_waitcnt lgkmcnt(0)
	s_barrier
	ds_read_b32 v2, v2
	s_mov_b64 s[22:23], 0
	v_readfirstlane_b32 s24, v0
	s_waitcnt lgkmcnt(0)
	s_barrier
	v_cmp_lt_i32_e32 vcc, s46, v2
	v_readfirstlane_b32 s14, v2
	s_cbranch_vccnz .LBB0_1739
	s_and_saveexec_b64 s[22:23], s[8:9]
	s_cbranch_execz .LBB0_1737
	s_mov_b64 s[26:27], exec
	v_mbcnt_lo_u32_b32 v2, s26, 0
	v_mbcnt_hi_u32_b32 v2, s27, v2
	v_cmp_eq_u32_e32 vcc, 0, v2
	s_and_saveexec_b64 s[24:25], vcc
	s_cbranch_execz .LBB0_1736
	s_bcnt1_i32_b64 s26, s[26:27]
	s_lshl_b32 s26, s26, 3
	v_mov_b32_e32 v3, s26
	global_atomic_add v254, v69, v3, s[2:3] sc0
.LBB0_1736:
	s_or_b64 exec, exec, s[24:25]
.LBB0_1737:
	s_or_b64 exec, exec, s[22:23]
	v_readlane_b32 s22, v248, 8
	s_add_i32 s24, s14, s22
